# SSM pass 2 tanh-gelu: polynomial constants folded into one fma (arg = y*(C1*y^2 + C0)), 7 VALU per value instead of 9
# speedup vs baseline: 1.0078x; 1.0078x over previous
.LBB0_509:
	v_mfma_f32_32x32x16_bf16 v[50:65], v[138:141], v[78:81], 0
	s_add_i32 s76, s76, 1
	v_lshl_add_u64 v[158:159], v[158:159], 0, s[70:71]
	s_cmp_eq_u32 s76, 16
	v_mfma_f32_32x32x16_bf16 v[2:17], v[138:141], v[66:69], 0
	v_mfma_f32_32x32x16_bf16 v[18:33], v[138:141], v[70:73], 0
	v_mfma_f32_32x32x16_bf16 v[34:49], v[138:141], v[74:77], 0
	v_xor_b32_e32 v254, 0x80000000, v156
	v_xor_b32_e32 v255, 0x80000000, v157
	s_nop 9
	v_fmac_f32_e32 v50, v160, v162
	v_fmac_f32_e32 v2, v161, v163
	v_fmac_f32_e32 v18, v160, v164
	v_fmac_f32_e32 v34, v161, v165
	v_fmac_f32_e32 v50, v254, v164
	v_fmac_f32_e32 v2, v255, v165
	v_fmac_f32_e32 v18, v156, v162
	v_fmac_f32_e32 v34, v157, v163
	v_fmac_f32_e32 v51, v160, v50
	v_fmac_f32_e32 v3, v161, v2
	v_fmac_f32_e32 v19, v160, v18
	v_fmac_f32_e32 v35, v161, v34
	v_fmac_f32_e32 v51, v254, v18
	v_fmac_f32_e32 v3, v255, v34
	v_fmac_f32_e32 v19, v156, v50
	v_fmac_f32_e32 v35, v157, v2
	v_fmac_f32_e32 v52, v160, v51
	v_fmac_f32_e32 v4, v161, v3
	v_fmac_f32_e32 v20, v160, v19
	v_fmac_f32_e32 v36, v161, v35
	v_fmac_f32_e32 v52, v254, v19
	v_fmac_f32_e32 v4, v255, v35
	v_fmac_f32_e32 v20, v156, v51
	v_fmac_f32_e32 v36, v157, v3
	v_fmac_f32_e32 v53, v160, v52
	v_fmac_f32_e32 v5, v161, v4
	v_fmac_f32_e32 v21, v160, v20
	v_fmac_f32_e32 v37, v161, v36
	v_fmac_f32_e32 v53, v254, v20
	v_fmac_f32_e32 v5, v255, v36
	v_fmac_f32_e32 v21, v156, v52
	v_fmac_f32_e32 v37, v157, v4
	v_fmac_f32_e32 v54, v160, v53
	v_fmac_f32_e32 v6, v161, v5
	v_fmac_f32_e32 v22, v160, v21
	v_fmac_f32_e32 v38, v161, v37
	v_fmac_f32_e32 v54, v254, v21
	v_fmac_f32_e32 v6, v255, v37
	v_fmac_f32_e32 v22, v156, v53
	v_fmac_f32_e32 v38, v157, v5
	v_fmac_f32_e32 v55, v160, v54
	v_fmac_f32_e32 v7, v161, v6
	v_fmac_f32_e32 v23, v160, v22
	v_fmac_f32_e32 v39, v161, v38
	v_fmac_f32_e32 v55, v254, v22
	v_fmac_f32_e32 v7, v255, v38
	v_fmac_f32_e32 v23, v156, v54
	v_fmac_f32_e32 v39, v157, v6
	v_fmac_f32_e32 v56, v160, v55
	v_fmac_f32_e32 v8, v161, v7
	v_fmac_f32_e32 v24, v160, v23
	v_fmac_f32_e32 v40, v161, v39
	v_fmac_f32_e32 v56, v254, v23
	v_fmac_f32_e32 v8, v255, v39
	v_fmac_f32_e32 v24, v156, v55
	v_fmac_f32_e32 v40, v157, v7
	v_fmac_f32_e32 v57, v160, v56
	v_fmac_f32_e32 v9, v161, v8
	v_fmac_f32_e32 v25, v160, v24
	v_fmac_f32_e32 v41, v161, v40
	v_fmac_f32_e32 v57, v254, v24
	v_fmac_f32_e32 v9, v255, v40
	v_fmac_f32_e32 v25, v156, v56
	v_fmac_f32_e32 v41, v157, v8
	v_fmac_f32_e32 v58, v160, v57
	v_fmac_f32_e32 v10, v161, v9
	v_fmac_f32_e32 v26, v160, v25
	v_fmac_f32_e32 v42, v161, v41
	v_fmac_f32_e32 v58, v254, v25
	v_fmac_f32_e32 v10, v255, v41
	v_fmac_f32_e32 v26, v156, v57
	v_fmac_f32_e32 v42, v157, v9
	v_fmac_f32_e32 v59, v160, v58
	v_fmac_f32_e32 v11, v161, v10
	v_fmac_f32_e32 v27, v160, v26
	v_fmac_f32_e32 v43, v161, v42
	v_fmac_f32_e32 v59, v254, v26
	v_fmac_f32_e32 v11, v255, v42
	v_fmac_f32_e32 v27, v156, v58
	v_fmac_f32_e32 v43, v157, v10
	v_fmac_f32_e32 v60, v160, v59
	v_fmac_f32_e32 v12, v161, v11
	v_fmac_f32_e32 v28, v160, v27
	v_fmac_f32_e32 v44, v161, v43
	v_fmac_f32_e32 v60, v254, v27
	v_fmac_f32_e32 v12, v255, v43
	v_fmac_f32_e32 v28, v156, v59
	v_fmac_f32_e32 v44, v157, v11
	v_fmac_f32_e32 v61, v160, v60
	v_fmac_f32_e32 v13, v161, v12
	v_fmac_f32_e32 v29, v160, v28
	v_fmac_f32_e32 v45, v161, v44
	v_fmac_f32_e32 v61, v254, v28
	v_fmac_f32_e32 v13, v255, v44
	v_fmac_f32_e32 v29, v156, v60
	v_fmac_f32_e32 v45, v157, v12
	v_fmac_f32_e32 v62, v160, v61
	v_fmac_f32_e32 v14, v161, v13
	v_fmac_f32_e32 v30, v160, v29
	v_fmac_f32_e32 v46, v161, v45
	v_fmac_f32_e32 v62, v254, v29
	v_fmac_f32_e32 v14, v255, v45
	v_fmac_f32_e32 v30, v156, v61
	v_fmac_f32_e32 v46, v157, v13
	v_fmac_f32_e32 v63, v160, v62
	v_fmac_f32_e32 v15, v161, v14
	v_fmac_f32_e32 v31, v160, v30
	v_fmac_f32_e32 v47, v161, v46
	v_fmac_f32_e32 v63, v254, v30
	v_fmac_f32_e32 v15, v255, v46
	v_fmac_f32_e32 v31, v156, v62
	v_fmac_f32_e32 v47, v157, v14
	v_fmac_f32_e32 v64, v160, v63
	v_fmac_f32_e32 v16, v161, v15
	v_fmac_f32_e32 v32, v160, v31
	v_fmac_f32_e32 v48, v161, v47
	v_fmac_f32_e32 v64, v254, v31
	v_fmac_f32_e32 v16, v255, v47
	v_fmac_f32_e32 v32, v156, v63
	v_fmac_f32_e32 v48, v157, v15
	v_fmac_f32_e32 v65, v160, v64
	v_fmac_f32_e32 v17, v161, v16
	v_fmac_f32_e32 v33, v160, v32
	v_fmac_f32_e32 v49, v161, v48
	v_fmac_f32_e32 v65, v254, v32
	v_fmac_f32_e32 v17, v255, v48
	v_fmac_f32_e32 v33, v156, v64
	v_fmac_f32_e32 v49, v157, v16
	v_mov_b32_e32 v162, v65
	v_mov_b32_e32 v163, v17
	v_mov_b32_e32 v164, v33
	v_mov_b32_e32 v165, v49
	v_cvt_pk_bf16_f32 v250, v2, v3
	v_cvt_pk_bf16_f32 v251, v4, v5
	ds_write_b64 v185, v[250:251] offset:2304
	v_cvt_pk_bf16_f32 v252, v6, v7
	v_cvt_pk_bf16_f32 v253, v8, v9
	ds_write_b64 v185, v[252:253] offset:2320
	v_cvt_pk_bf16_f32 v250, v10, v11
	v_cvt_pk_bf16_f32 v251, v12, v13
	ds_write_b64 v185, v[250:251] offset:2336
	v_cvt_pk_bf16_f32 v252, v14, v15
	v_cvt_pk_bf16_f32 v253, v16, v17
	ds_write_b64 v185, v[252:253] offset:2352
	v_mfma_f32_32x32x16_bf16 v[2:17], v[94:97], v[138:141], 0
	v_cvt_pk_bf16_f32 v250, v50, v51
	v_cvt_pk_bf16_f32 v251, v52, v53
	ds_write_b64 v185, v[250:251]
	v_cvt_pk_bf16_f32 v252, v54, v55
	v_cvt_pk_bf16_f32 v253, v56, v57
	ds_write_b64 v185, v[252:253] offset:16
	v_cvt_pk_bf16_f32 v250, v58, v59
	v_cvt_pk_bf16_f32 v251, v60, v61
	ds_write_b64 v185, v[250:251] offset:32
	v_cvt_pk_bf16_f32 v252, v62, v63
	v_cvt_pk_bf16_f32 v253, v64, v65
	ds_write_b64 v185, v[252:253] offset:48
	v_mfma_f32_32x32x16_bf16 v[2:17], v[98:101], v[138:141], v[2:17]
	v_cvt_pk_bf16_f32 v250, v18, v19
	v_cvt_pk_bf16_f32 v251, v20, v21
	ds_write_b64 v185, v[250:251] offset:4608
	v_cvt_pk_bf16_f32 v252, v22, v23
	v_cvt_pk_bf16_f32 v253, v24, v25
	ds_write_b64 v185, v[252:253] offset:4624
	v_cvt_pk_bf16_f32 v250, v26, v27
	v_cvt_pk_bf16_f32 v251, v28, v29
	ds_write_b64 v185, v[250:251] offset:4640
	v_cvt_pk_bf16_f32 v252, v30, v31
	v_cvt_pk_bf16_f32 v253, v32, v33
	ds_write_b64 v185, v[252:253] offset:4656
	v_cvt_pk_bf16_f32 v250, v34, v35
	v_cvt_pk_bf16_f32 v251, v36, v37
	ds_write_b64 v185, v[250:251] offset:6912
	v_cvt_pk_bf16_f32 v252, v38, v39
	v_cvt_pk_bf16_f32 v253, v40, v41
	ds_write_b64 v185, v[252:253] offset:6928
	v_cvt_pk_bf16_f32 v250, v42, v43
	v_cvt_pk_bf16_f32 v251, v44, v45
	ds_write_b64 v185, v[250:251] offset:6944
	v_cvt_pk_bf16_f32 v252, v46, v47
	v_cvt_pk_bf16_f32 v253, v48, v49
	ds_write_b64 v185, v[252:253] offset:6960
	s_waitcnt lgkmcnt(0)
	ds_read_b64_tr_b16 v[18:19], v186
	ds_read_b64_tr_b16 v[20:21], v186 offset:288
	ds_read_b64_tr_b16 v[22:23], v186 offset:1152
	ds_read_b64_tr_b16 v[24:25], v186 offset:1440
	v_mov_b64_e32 v[140:141], v[136:137]
	v_mov_b64_e32 v[138:139], v[134:135]
	s_waitcnt lgkmcnt(2)
	v_mfma_f32_32x32x16_bf16 v[2:17], v[102:105], v[18:21], v[2:17]
	s_waitcnt lgkmcnt(0)
	v_mfma_f32_32x32x16_bf16 v[2:17], v[106:109], v[22:25], v[2:17]
	ds_read_b64_tr_b16 v[18:19], v186 offset:2304
	ds_read_b64_tr_b16 v[20:21], v186 offset:2592
	ds_read_b64_tr_b16 v[22:23], v186 offset:3456
	ds_read_b64_tr_b16 v[24:25], v186 offset:3744
	s_waitcnt lgkmcnt(2)
	v_mfma_f32_32x32x16_bf16 v[2:17], v[110:113], v[18:21], v[2:17]
	s_waitcnt lgkmcnt(0)
	v_mfma_f32_32x32x16_bf16 v[2:17], v[114:117], v[22:25], v[2:17]
	ds_read_b64_tr_b16 v[18:19], v186 offset:4608
	ds_read_b64_tr_b16 v[20:21], v186 offset:4896
	ds_read_b64_tr_b16 v[22:23], v186 offset:5760
	ds_read_b64_tr_b16 v[24:25], v186 offset:6048
	s_waitcnt lgkmcnt(2)
	v_mfma_f32_32x32x16_bf16 v[2:17], v[118:121], v[18:21], v[2:17]
	s_waitcnt lgkmcnt(0)
	v_mfma_f32_32x32x16_bf16 v[2:17], v[122:125], v[22:25], v[2:17]
	ds_read_b64_tr_b16 v[18:19], v186 offset:6912
	ds_read_b64_tr_b16 v[20:21], v186 offset:7200
	ds_read_b64_tr_b16 v[22:23], v186 offset:8064
	ds_read_b64_tr_b16 v[24:25], v186 offset:8352
	s_waitcnt lgkmcnt(0)
	s_waitcnt lgkmcnt(2)
	v_mfma_f32_32x32x16_bf16 v[2:17], v[126:129], v[18:21], v[2:17]
	s_waitcnt lgkmcnt(0)
	v_mfma_f32_32x32x16_bf16 v[2:17], v[130:133], v[22:25], v[2:17]
	s_nop 11
	v_mov_b32_e32 v249, 0xbdd2d3e8
	v_mul_f32_e32 v10, v2, v2
	v_mul_f32_e32 v11, v3, v3
	v_mul_f32_e32 v12, v4, v4
	v_mul_f32_e32 v13, v5, v5
	v_mul_f32_e32 v14, v6, v6
	v_mul_f32_e32 v15, v7, v7
	v_mul_f32_e32 v16, v8, v8
	v_mul_f32_e32 v17, v9, v9
	v_fmaak_f32 v10, v249, v10, 0xc0135761
	v_fmaak_f32 v11, v249, v11, 0xc0135761
	v_fmaak_f32 v12, v249, v12, 0xc0135761
	v_fmaak_f32 v13, v249, v13, 0xc0135761
	v_fmaak_f32 v14, v249, v14, 0xc0135761
	v_fmaak_f32 v15, v249, v15, 0xc0135761
	v_fmaak_f32 v16, v249, v16, 0xc0135761
	v_fmaak_f32 v17, v249, v17, 0xc0135761
	v_mul_f32_e32 v10, v2, v10
	v_mul_f32_e32 v11, v3, v11
	v_mul_f32_e32 v12, v4, v12
	v_mul_f32_e32 v13, v5, v13
	v_mul_f32_e32 v14, v6, v14
	v_mul_f32_e32 v15, v7, v15
	v_mul_f32_e32 v16, v8, v16
	v_mul_f32_e32 v17, v9, v17
	v_exp_f32_e32 v10, v10
	v_exp_f32_e32 v11, v11
	v_exp_f32_e32 v12, v12
	v_exp_f32_e32 v13, v13
	v_exp_f32_e32 v14, v14
	v_exp_f32_e32 v15, v15
	v_exp_f32_e32 v16, v16
	v_exp_f32_e32 v17, v17
	v_add_f32_e32 v10, 1.0, v10
	v_add_f32_e32 v11, 1.0, v11
	v_add_f32_e32 v12, 1.0, v12
	v_add_f32_e32 v13, 1.0, v13
	v_add_f32_e32 v14, 1.0, v14
	v_add_f32_e32 v15, 1.0, v15
	v_add_f32_e32 v16, 1.0, v16
	v_add_f32_e32 v17, 1.0, v17
	v_rcp_f32_e32 v10, v10
	v_rcp_f32_e32 v11, v11
	v_rcp_f32_e32 v12, v12
	v_rcp_f32_e32 v13, v13
	v_rcp_f32_e32 v14, v14
	v_rcp_f32_e32 v15, v15
	v_rcp_f32_e32 v16, v16
	v_rcp_f32_e32 v17, v17
	v_mul_f32_e32 v2, v2, v10
	v_mul_f32_e32 v3, v3, v11
	v_mul_f32_e32 v4, v4, v12
	v_mul_f32_e32 v5, v5, v13
	v_mul_f32_e32 v6, v6, v14
	v_mul_f32_e32 v7, v7, v15
	v_mul_f32_e32 v8, v8, v16
	v_mul_f32_e32 v9, v9, v17
	v_cvt_pk_bf16_f32 v2, v2, v3
	v_cvt_pk_bf16_f32 v3, v4, v5
	v_cvt_pk_bf16_f32 v4, v6, v7
	v_cvt_pk_bf16_f32 v5, v8, v9
	global_store_dwordx2 v[168:169], v[2:3], off
	global_store_dwordx2 v[168:169], v[4:5], off offset:16
	v_lshl_add_u64 v[168:169], v[168:169], 0, s[70:71]
	s_cbranch_scc1 .LBB0_493
	s_waitcnt vmcnt(2)
	v_mov_b64_e32 v[136:137], v[84:85]
	v_mov_b64_e32 v[134:135], v[82:83]
	v_mov_b64_e32 v[82:83], v[90:91]
	v_mov_b64_e32 v[84:85], v[92:93]
	v_mov_b64_e32 v[92:93], v[88:89]
	s_cmp_gt_u32 s76, 11
	v_mov_b64_e32 v[90:91], v[86:87]
	s_cbranch_scc1 .LBB0_509
	s_branch .Lssm2_load
